# v006 + v_rsq_f32 in FFN-up epilogue (was exact sqrt+div expansion, 8 per lane) + band-prompt QK reads up front + FS cs-load hoist
# speedup vs baseline: 1.0018x; 1.0018x over previous
.LBB0_959:
	v_lshl_add_u32 v146, s4, 8, v1
	v_ashrrev_i32_e32 v147, 31, v146
	v_lshl_add_u64 v[166:167], v[146:147], 2, s[14:15]
	v_or_b32_e32 v154, 16, v146
	global_load_dword v172, v[166:167], off
	v_ashrrev_i32_e32 v155, 31, v154
	v_lshl_add_u64 v[148:149], v[154:155], 2, s[14:15]
	global_load_dword v173, v[148:149], off
	v_or_b32_e32 v148, 48, v146
	v_or_b32_e32 v152, 32, v146
	v_ashrrev_i32_e32 v149, 31, v148
	v_ashrrev_i32_e32 v153, 31, v152
	v_lshl_add_u64 v[170:171], v[148:149], 2, s[14:15]
	v_lshl_add_u64 v[168:169], v[152:153], 2, s[14:15]
	global_load_dword v174, v[166:167], off offset:512
	global_load_dword v165, v[166:167], off offset:576
	global_load_dword v164, v[166:167], off offset:640
	global_load_dword v175, v[168:169], off
	s_nop 0
	global_load_dword v170, v[170:171], off
	s_nop 0
	global_load_dword v163, v[166:167], off offset:704
	v_lshl_or_b32 v150, s5, 8, v157
	v_ashrrev_i32_e32 v151, 31, v150
	v_lshl_add_u64 v[150:151], v[150:151], 1, s[16:17]
	v_lshlrev_b64 v[146:147], 13, v[146:147]
	v_lshl_add_u64 v[146:147], v[150:151], 0, v[146:147]
	s_waitcnt vmcnt(0)
	v_fmamk_f32 v166, v172, 0x3a800000, v161
	v_fmamk_f32 v168, v173, 0x3a800000, v161
	v_rsq_f32_e32 v166, v166
	v_rsq_f32_e32 v167, v168
	s_nop 1
	s_nop 0
	v_mov_b32_e32 v166, v166
	s_nop 0
	v_mov_b32_e32 v172, v167
	v_mov_b32_e32 v166, v166
	v_pk_mul_f32 v[128:129], v[128:129], v[166:167] op_sel_hi:[1,0]
	v_pk_mul_f32 v[126:127], v[126:127], v[166:167] op_sel_hi:[1,0]
	v_pk_mul_f32 v[124:125], v[124:125], v[166:167] op_sel_hi:[1,0]
	v_pk_mul_f32 v[122:123], v[122:123], v[166:167] op_sel_hi:[1,0]
	v_pk_mul_f32 v[116:117], v[116:117], v[166:167] op_sel_hi:[1,0]
	v_pk_mul_f32 v[114:115], v[114:115], v[166:167] op_sel_hi:[1,0]
	v_max_f32_e32 v126, 0, v126
	v_max_f32_e32 v122, 0, v122
	v_max_f32_e32 v127, 0, v127
	v_max_f32_e32 v123, 0, v123
	v_max_f32_e32 v128, 0, v128
	v_max_f32_e32 v124, 0, v124
	v_max_f32_e32 v129, 0, v129
	v_max_f32_e32 v125, 0, v125
	v_max_f32_e32 v114, 0, v114
	v_max_f32_e32 v115, 0, v115
	v_max_f32_e32 v116, 0, v116
	v_max_f32_e32 v117, 0, v117
	v_pk_mul_f32 v[126:127], v[126:127], v[126:127]
	v_pk_mul_f32 v[122:123], v[122:123], v[122:123]
	v_pk_mul_f32 v[128:129], v[128:129], v[128:129]
	v_pk_mul_f32 v[124:125], v[124:125], v[124:125]
	v_pk_mul_f32 v[120:121], v[120:121], v[166:167] op_sel_hi:[1,0]
	v_pk_mul_f32 v[118:119], v[118:119], v[166:167] op_sel_hi:[1,0]
	v_pk_mul_f32 v[166:167], v[114:115], v[114:115]
	v_pk_mul_f32 v[168:169], v[116:117], v[116:117]
	v_cvt_pk_bf16_f32 v114, v126, v127
	v_cvt_pk_bf16_f32 v115, v128, v129
	v_cvt_pk_bf16_f32 v116, v122, v123
	v_cvt_pk_bf16_f32 v117, v124, v125
	global_store_dwordx4 v[146:147], v[114:117], off
	v_max_f32_e32 v118, 0, v118
	v_max_f32_e32 v119, 0, v119
	v_max_f32_e32 v120, 0, v120
	v_max_f32_e32 v121, 0, v121
	v_mov_b32_e32 v114, v172
	v_pk_mul_f32 v[118:119], v[118:119], v[118:119]
	v_pk_mul_f32 v[120:121], v[120:121], v[120:121]
	v_pk_mul_f32 v[106:107], v[106:107], v[114:115] op_sel_hi:[1,0]
	v_cvt_pk_bf16_f32 v118, v118, v119
	v_cvt_pk_bf16_f32 v119, v120, v121
	v_cvt_pk_bf16_f32 v120, v166, v167
	v_cvt_pk_bf16_f32 v121, v168, v169
	v_pk_mul_f32 v[112:113], v[112:113], v[114:115] op_sel_hi:[1,0]
	v_pk_mul_f32 v[110:111], v[110:111], v[114:115] op_sel_hi:[1,0]
	v_pk_mul_f32 v[108:109], v[108:109], v[114:115] op_sel_hi:[1,0]
	v_max_f32_e32 v106, 0, v106
	v_max_f32_e32 v107, 0, v107
	global_store_dwordx4 v[146:147], v[118:121], off offset:256
	v_max_f32_e32 v110, 0, v110
	v_max_f32_e32 v111, 0, v111
	v_pk_mul_f32 v[118:119], v[106:107], v[106:107]
	v_max_f32_e32 v106, 0, v112
	v_max_f32_e32 v108, 0, v108
	v_max_f32_e32 v107, 0, v113
	v_max_f32_e32 v109, 0, v109
	v_lshlrev_b64 v[116:117], 13, v[154:155]
	v_pk_mul_f32 v[110:111], v[110:111], v[110:111]
	v_pk_mul_f32 v[112:113], v[106:107], v[106:107]
	v_pk_mul_f32 v[120:121], v[108:109], v[108:109]
	v_pk_mul_f32 v[98:99], v[98:99], v[114:115] op_sel_hi:[1,0]
	v_lshl_add_u64 v[116:117], v[150:151], 0, v[116:117]
	v_cvt_pk_bf16_f32 v106, v110, v111
	v_cvt_pk_bf16_f32 v107, v112, v113
	v_cvt_pk_bf16_f32 v108, v118, v119
	v_cvt_pk_bf16_f32 v109, v120, v121
	v_pk_mul_f32 v[104:105], v[104:105], v[114:115] op_sel_hi:[1,0]
	v_max_f32_e32 v98, 0, v98
	v_max_f32_e32 v99, 0, v99
	global_store_dwordx4 v[116:117], v[106:109], off
	v_pk_mul_f32 v[100:101], v[100:101], v[114:115] op_sel_hi:[1,0]
	v_pk_mul_f32 v[102:103], v[102:103], v[114:115] op_sel_hi:[1,0]
	v_pk_mul_f32 v[106:107], v[98:99], v[98:99]
	v_max_f32_e32 v98, 0, v104
	v_max_f32_e32 v99, 0, v105
	v_pk_mul_f32 v[104:105], v[98:99], v[98:99]
	v_fmamk_f32 v98, v175, 0x3a800000, v161
	v_max_f32_e32 v100, 0, v100
	v_max_f32_e32 v101, 0, v101
	v_rsq_f32_e32 v110, v98
	v_pk_mul_f32 v[108:109], v[100:101], v[100:101]
	v_max_f32_e32 v102, 0, v102
	v_max_f32_e32 v103, 0, v103
	v_pk_mul_f32 v[102:103], v[102:103], v[102:103]
	v_cvt_pk_bf16_f32 v98, v102, v103
	v_cvt_pk_bf16_f32 v99, v104, v105
	s_nop 0
	v_cvt_pk_bf16_f32 v101, v108, v109
	s_nop 0
	v_mov_b32_e32 v102, v110
	v_cvt_pk_bf16_f32 v100, v106, v107
	global_store_dwordx4 v[116:117], v[98:101], off offset:256
	s_nop 1
	v_mov_b32_e32 v98, v102
	v_pk_mul_f32 v[90:91], v[90:91], v[98:99] op_sel_hi:[1,0]
	v_pk_mul_f32 v[96:97], v[96:97], v[98:99] op_sel_hi:[1,0]
	v_pk_mul_f32 v[94:95], v[94:95], v[98:99] op_sel_hi:[1,0]
	v_pk_mul_f32 v[92:93], v[92:93], v[98:99] op_sel_hi:[1,0]
	v_max_f32_e32 v90, 0, v90
	v_max_f32_e32 v91, 0, v91
	v_max_f32_e32 v94, 0, v94
	v_max_f32_e32 v95, 0, v95
	v_pk_mul_f32 v[102:103], v[90:91], v[90:91]
	v_max_f32_e32 v90, 0, v96
	v_max_f32_e32 v92, 0, v92
	v_max_f32_e32 v91, 0, v97
	v_max_f32_e32 v93, 0, v93
	v_lshlrev_b64 v[100:101], 13, v[152:153]
	v_pk_mul_f32 v[94:95], v[94:95], v[94:95]
	v_pk_mul_f32 v[96:97], v[90:91], v[90:91]
	v_pk_mul_f32 v[104:105], v[92:93], v[92:93]
	v_pk_mul_f32 v[82:83], v[82:83], v[98:99] op_sel_hi:[1,0]
	v_lshl_add_u64 v[100:101], v[150:151], 0, v[100:101]
	v_cvt_pk_bf16_f32 v90, v94, v95
	v_cvt_pk_bf16_f32 v91, v96, v97
	v_cvt_pk_bf16_f32 v92, v102, v103
	v_cvt_pk_bf16_f32 v93, v104, v105
	v_pk_mul_f32 v[88:89], v[88:89], v[98:99] op_sel_hi:[1,0]
	v_max_f32_e32 v82, 0, v82
	v_max_f32_e32 v83, 0, v83
	global_store_dwordx4 v[100:101], v[90:93], off
	v_pk_mul_f32 v[84:85], v[84:85], v[98:99] op_sel_hi:[1,0]
	v_pk_mul_f32 v[86:87], v[86:87], v[98:99] op_sel_hi:[1,0]
	v_pk_mul_f32 v[90:91], v[82:83], v[82:83]
	v_max_f32_e32 v82, 0, v88
	v_max_f32_e32 v83, 0, v89
	v_pk_mul_f32 v[88:89], v[82:83], v[82:83]
	v_fmamk_f32 v82, v170, 0x3a800000, v161
	v_max_f32_e32 v84, 0, v84
	v_max_f32_e32 v85, 0, v85
	v_rsq_f32_e32 v94, v82
	v_pk_mul_f32 v[92:93], v[84:85], v[84:85]
	v_max_f32_e32 v86, 0, v86
	v_max_f32_e32 v87, 0, v87
	v_pk_mul_f32 v[86:87], v[86:87], v[86:87]
	v_cvt_pk_bf16_f32 v82, v86, v87
	v_cvt_pk_bf16_f32 v83, v88, v89
	s_nop 0
	v_cvt_pk_bf16_f32 v85, v92, v93
	s_nop 0
	v_mov_b32_e32 v86, v94
	v_cvt_pk_bf16_f32 v84, v90, v91
	global_store_dwordx4 v[100:101], v[82:85], off offset:256
	s_nop 1
	v_mov_b32_e32 v82, v86
	v_pk_mul_f32 v[74:75], v[74:75], v[82:83] op_sel_hi:[1,0]
	v_pk_mul_f32 v[80:81], v[80:81], v[82:83] op_sel_hi:[1,0]
	v_pk_mul_f32 v[78:79], v[78:79], v[82:83] op_sel_hi:[1,0]
	v_pk_mul_f32 v[76:77], v[76:77], v[82:83] op_sel_hi:[1,0]
	v_max_f32_e32 v74, 0, v74
	v_max_f32_e32 v75, 0, v75
	v_max_f32_e32 v78, 0, v78
	v_max_f32_e32 v79, 0, v79
	v_pk_mul_f32 v[86:87], v[74:75], v[74:75]
	v_max_f32_e32 v74, 0, v80
	v_max_f32_e32 v76, 0, v76
	v_max_f32_e32 v75, 0, v81
	v_max_f32_e32 v77, 0, v77
	v_lshlrev_b64 v[84:85], 13, v[148:149]
	v_pk_mul_f32 v[78:79], v[78:79], v[78:79]
	v_pk_mul_f32 v[80:81], v[74:75], v[74:75]
	v_pk_mul_f32 v[88:89], v[76:77], v[76:77]
	v_pk_mul_f32 v[66:67], v[66:67], v[82:83] op_sel_hi:[1,0]
	v_lshl_add_u64 v[84:85], v[150:151], 0, v[84:85]
	v_cvt_pk_bf16_f32 v74, v78, v79
	v_cvt_pk_bf16_f32 v75, v80, v81
	v_cvt_pk_bf16_f32 v76, v86, v87
	v_cvt_pk_bf16_f32 v77, v88, v89
	v_pk_mul_f32 v[72:73], v[72:73], v[82:83] op_sel_hi:[1,0]
	v_max_f32_e32 v66, 0, v66
	v_max_f32_e32 v67, 0, v67
	global_store_dwordx4 v[84:85], v[74:77], off
	v_pk_mul_f32 v[68:69], v[68:69], v[82:83] op_sel_hi:[1,0]
	v_pk_mul_f32 v[70:71], v[70:71], v[82:83] op_sel_hi:[1,0]
	v_pk_mul_f32 v[74:75], v[66:67], v[66:67]
	v_max_f32_e32 v66, 0, v72
	v_max_f32_e32 v67, 0, v73
	v_pk_mul_f32 v[72:73], v[66:67], v[66:67]
	v_fmamk_f32 v66, v174, 0x3a800000, v161
	v_max_f32_e32 v68, 0, v68
	v_max_f32_e32 v69, 0, v69
	v_rsq_f32_e32 v78, v66
	v_pk_mul_f32 v[76:77], v[68:69], v[68:69]
	v_max_f32_e32 v70, 0, v70
	v_max_f32_e32 v71, 0, v71
	v_pk_mul_f32 v[70:71], v[70:71], v[70:71]
	v_cvt_pk_bf16_f32 v66, v70, v71
	v_cvt_pk_bf16_f32 v67, v72, v73
	s_nop 0
	v_cvt_pk_bf16_f32 v69, v76, v77
	s_nop 0
	v_mov_b32_e32 v70, v78
	v_cvt_pk_bf16_f32 v68, v74, v75
	global_store_dwordx4 v[84:85], v[66:69], off offset:256
	s_nop 1
	v_mov_b32_e32 v66, v70
	v_pk_mul_f32 v[62:63], v[62:63], v[66:67] op_sel_hi:[1,0]
	v_pk_mul_f32 v[58:59], v[58:59], v[66:67] op_sel_hi:[1,0]
	v_pk_mul_f32 v[64:65], v[64:65], v[66:67] op_sel_hi:[1,0]
	v_pk_mul_f32 v[60:61], v[60:61], v[66:67] op_sel_hi:[1,0]
	v_max_f32_e32 v62, 0, v62
	v_max_f32_e32 v58, 0, v58
	v_max_f32_e32 v63, 0, v63
	v_max_f32_e32 v59, 0, v59
	v_pk_mul_f32 v[62:63], v[62:63], v[62:63]
	v_pk_mul_f32 v[70:71], v[58:59], v[58:59]
	v_max_f32_e32 v58, 0, v64
	v_max_f32_e32 v60, 0, v60
	v_max_f32_e32 v59, 0, v65
	v_max_f32_e32 v61, 0, v61
	v_pk_mul_f32 v[64:65], v[58:59], v[58:59]
	v_pk_mul_f32 v[72:73], v[60:61], v[60:61]
	v_cvt_pk_bf16_f32 v58, v62, v63
	v_add_co_u32_e32 v62, vcc, s57, v146
	v_pk_mul_f32 v[50:51], v[50:51], v[66:67] op_sel_hi:[1,0]
	v_cvt_pk_bf16_f32 v59, v64, v65
	v_cvt_pk_bf16_f32 v60, v70, v71
	v_cvt_pk_bf16_f32 v61, v72, v73
	v_addc_co_u32_e32 v63, vcc, 0, v147, vcc
	v_pk_mul_f32 v[56:57], v[56:57], v[66:67] op_sel_hi:[1,0]
	v_max_f32_e32 v50, 0, v50
	v_max_f32_e32 v51, 0, v51
	global_store_dwordx4 v[62:63], v[58:61], off
	v_pk_mul_f32 v[52:53], v[52:53], v[66:67] op_sel_hi:[1,0]
	v_pk_mul_f32 v[54:55], v[54:55], v[66:67] op_sel_hi:[1,0]
	v_pk_mul_f32 v[58:59], v[50:51], v[50:51]
	v_max_f32_e32 v50, 0, v56
	v_max_f32_e32 v51, 0, v57
	v_pk_mul_f32 v[56:57], v[50:51], v[50:51]
	v_fmamk_f32 v50, v165, 0x3a800000, v161
	v_max_f32_e32 v52, 0, v52
	v_max_f32_e32 v53, 0, v53
	v_rsq_f32_e32 v62, v50
	v_pk_mul_f32 v[60:61], v[52:53], v[52:53]
	v_max_f32_e32 v54, 0, v54
	v_max_f32_e32 v55, 0, v55
	v_pk_mul_f32 v[54:55], v[54:55], v[54:55]
	v_cvt_pk_bf16_f32 v50, v54, v55
	v_cvt_pk_bf16_f32 v51, v56, v57
	v_lshl_add_u64 v[68:69], v[146:147], 0, s[18:19]
	v_cvt_pk_bf16_f32 v53, v60, v61
	s_nop 0
	v_mov_b32_e32 v54, v62
	v_cvt_pk_bf16_f32 v52, v58, v59
	global_store_dwordx4 v[68:69], v[50:53], off offset:256
	s_nop 1
	v_mov_b32_e32 v50, v54
	v_pk_mul_f32 v[46:47], v[46:47], v[50:51] op_sel_hi:[1,0]
	v_pk_mul_f32 v[42:43], v[42:43], v[50:51] op_sel_hi:[1,0]
	v_pk_mul_f32 v[48:49], v[48:49], v[50:51] op_sel_hi:[1,0]
	v_pk_mul_f32 v[44:45], v[44:45], v[50:51] op_sel_hi:[1,0]
	v_max_f32_e32 v46, 0, v46
	v_max_f32_e32 v42, 0, v42
	v_max_f32_e32 v47, 0, v47
	v_max_f32_e32 v43, 0, v43
	v_pk_mul_f32 v[46:47], v[46:47], v[46:47]
	v_pk_mul_f32 v[54:55], v[42:43], v[42:43]
	v_max_f32_e32 v42, 0, v48
	v_max_f32_e32 v44, 0, v44
	v_max_f32_e32 v43, 0, v49
	v_max_f32_e32 v45, 0, v45
	v_pk_mul_f32 v[48:49], v[42:43], v[42:43]
	v_pk_mul_f32 v[56:57], v[44:45], v[44:45]
	v_cvt_pk_bf16_f32 v42, v46, v47
	v_add_co_u32_e32 v46, vcc, s58, v146
	v_pk_mul_f32 v[34:35], v[34:35], v[50:51] op_sel_hi:[1,0]
	v_cvt_pk_bf16_f32 v43, v48, v49
	v_cvt_pk_bf16_f32 v44, v54, v55
	v_cvt_pk_bf16_f32 v45, v56, v57
	v_addc_co_u32_e32 v47, vcc, 0, v147, vcc
	v_pk_mul_f32 v[40:41], v[40:41], v[50:51] op_sel_hi:[1,0]
	v_max_f32_e32 v34, 0, v34
	v_max_f32_e32 v35, 0, v35
	global_store_dwordx4 v[46:47], v[42:45], off
	v_pk_mul_f32 v[36:37], v[36:37], v[50:51] op_sel_hi:[1,0]
	v_pk_mul_f32 v[38:39], v[38:39], v[50:51] op_sel_hi:[1,0]
	v_pk_mul_f32 v[42:43], v[34:35], v[34:35]
	v_max_f32_e32 v34, 0, v40
	v_max_f32_e32 v35, 0, v41
	v_pk_mul_f32 v[40:41], v[34:35], v[34:35]
	v_fmamk_f32 v34, v164, 0x3a800000, v161
	v_max_f32_e32 v36, 0, v36
	v_max_f32_e32 v37, 0, v37
	v_rsq_f32_e32 v46, v34
	v_pk_mul_f32 v[44:45], v[36:37], v[36:37]
	v_max_f32_e32 v38, 0, v38
	v_max_f32_e32 v39, 0, v39
	v_pk_mul_f32 v[38:39], v[38:39], v[38:39]
	v_cvt_pk_bf16_f32 v34, v38, v39
	v_cvt_pk_bf16_f32 v35, v40, v41
	v_lshl_add_u64 v[52:53], v[146:147], 0, s[20:21]
	v_cvt_pk_bf16_f32 v37, v44, v45
	s_nop 0
	v_mov_b32_e32 v38, v46
	v_cvt_pk_bf16_f32 v36, v42, v43
	global_store_dwordx4 v[52:53], v[34:37], off offset:256
	s_nop 1
	v_mov_b32_e32 v34, v38
	v_pk_mul_f32 v[30:31], v[30:31], v[34:35] op_sel_hi:[1,0]
	v_pk_mul_f32 v[26:27], v[26:27], v[34:35] op_sel_hi:[1,0]
	v_pk_mul_f32 v[32:33], v[32:33], v[34:35] op_sel_hi:[1,0]
	v_pk_mul_f32 v[28:29], v[28:29], v[34:35] op_sel_hi:[1,0]
	v_max_f32_e32 v30, 0, v30
	v_max_f32_e32 v26, 0, v26
	v_max_f32_e32 v31, 0, v31
	v_max_f32_e32 v27, 0, v27
	v_pk_mul_f32 v[30:31], v[30:31], v[30:31]
	v_pk_mul_f32 v[38:39], v[26:27], v[26:27]
	v_max_f32_e32 v26, 0, v32
	v_max_f32_e32 v28, 0, v28
	v_max_f32_e32 v27, 0, v33
	v_max_f32_e32 v29, 0, v29
	v_pk_mul_f32 v[32:33], v[26:27], v[26:27]
	v_pk_mul_f32 v[40:41], v[28:29], v[28:29]
	v_cvt_pk_bf16_f32 v26, v30, v31
	v_add_co_u32_e32 v30, vcc, s59, v146
	v_pk_mul_f32 v[18:19], v[18:19], v[34:35] op_sel_hi:[1,0]
	v_cvt_pk_bf16_f32 v27, v32, v33
	v_cvt_pk_bf16_f32 v28, v38, v39
	v_cvt_pk_bf16_f32 v29, v40, v41
	v_addc_co_u32_e32 v31, vcc, 0, v147, vcc
	v_pk_mul_f32 v[24:25], v[24:25], v[34:35] op_sel_hi:[1,0]
	v_max_f32_e32 v18, 0, v18
	v_max_f32_e32 v19, 0, v19
	global_store_dwordx4 v[30:31], v[26:29], off
	v_pk_mul_f32 v[20:21], v[20:21], v[34:35] op_sel_hi:[1,0]
	v_pk_mul_f32 v[22:23], v[22:23], v[34:35] op_sel_hi:[1,0]
	v_pk_mul_f32 v[26:27], v[18:19], v[18:19]
	v_max_f32_e32 v18, 0, v24
	v_max_f32_e32 v19, 0, v25
	v_pk_mul_f32 v[24:25], v[18:19], v[18:19]
	v_fmamk_f32 v18, v163, 0x3a800000, v161
	v_max_f32_e32 v20, 0, v20
	v_max_f32_e32 v21, 0, v21
	v_rsq_f32_e32 v30, v18
	v_pk_mul_f32 v[28:29], v[20:21], v[20:21]
	v_max_f32_e32 v22, 0, v22
	v_max_f32_e32 v23, 0, v23
	v_pk_mul_f32 v[22:23], v[22:23], v[22:23]
	v_cvt_pk_bf16_f32 v18, v22, v23
	v_cvt_pk_bf16_f32 v19, v24, v25
	v_lshl_add_u64 v[36:37], v[146:147], 0, s[22:23]
	v_cvt_pk_bf16_f32 v21, v28, v29
	s_nop 0
	v_mov_b32_e32 v22, v30
	v_cvt_pk_bf16_f32 v20, v26, v27
	global_store_dwordx4 v[36:37], v[18:21], off offset:256
	s_nop 1
	v_mov_b32_e32 v18, v22
	v_pk_mul_f32 v[14:15], v[14:15], v[18:19] op_sel_hi:[1,0]
	v_pk_mul_f32 v[10:11], v[10:11], v[18:19] op_sel_hi:[1,0]
	v_pk_mul_f32 v[16:17], v[16:17], v[18:19] op_sel_hi:[1,0]
	v_pk_mul_f32 v[12:13], v[12:13], v[18:19] op_sel_hi:[1,0]
	v_max_f32_e32 v14, 0, v14
	v_max_f32_e32 v10, 0, v10
	v_max_f32_e32 v15, 0, v15
	v_max_f32_e32 v11, 0, v11
	v_pk_mul_f32 v[14:15], v[14:15], v[14:15]
	v_pk_mul_f32 v[22:23], v[10:11], v[10:11]
	v_max_f32_e32 v10, 0, v16
	v_max_f32_e32 v12, 0, v12
	v_max_f32_e32 v11, 0, v17
	v_max_f32_e32 v13, 0, v13
	v_pk_mul_f32 v[16:17], v[10:11], v[10:11]
	v_pk_mul_f32 v[24:25], v[12:13], v[12:13]
	v_cvt_pk_bf16_f32 v10, v14, v15
	v_add_co_u32_e32 v14, vcc, s60, v146
	v_pk_mul_f32 v[2:3], v[2:3], v[18:19] op_sel_hi:[1,0]
	v_cvt_pk_bf16_f32 v11, v16, v17
	v_cvt_pk_bf16_f32 v12, v22, v23
	v_cvt_pk_bf16_f32 v13, v24, v25
	v_addc_co_u32_e32 v15, vcc, 0, v147, vcc
	v_pk_mul_f32 v[8:9], v[8:9], v[18:19] op_sel_hi:[1,0]
	v_pk_mul_f32 v[6:7], v[6:7], v[18:19] op_sel_hi:[1,0]
	v_pk_mul_f32 v[4:5], v[4:5], v[18:19] op_sel_hi:[1,0]
	v_max_f32_e32 v2, 0, v2
	v_max_f32_e32 v3, 0, v3
	global_store_dwordx4 v[14:15], v[10:13], off
	v_max_f32_e32 v6, 0, v6
	v_max_f32_e32 v7, 0, v7
	v_pk_mul_f32 v[10:11], v[2:3], v[2:3]
	v_max_f32_e32 v2, 0, v8
	v_max_f32_e32 v4, 0, v4
	v_max_f32_e32 v3, 0, v9
	v_max_f32_e32 v5, 0, v5
	v_pk_mul_f32 v[6:7], v[6:7], v[6:7]
	v_pk_mul_f32 v[8:9], v[2:3], v[2:3]
	v_pk_mul_f32 v[12:13], v[4:5], v[4:5]
	v_lshl_add_u64 v[20:21], v[146:147], 0, s[24:25]
	v_cvt_pk_bf16_f32 v2, v6, v7
	v_cvt_pk_bf16_f32 v3, v8, v9
	v_cvt_pk_bf16_f32 v4, v10, v11
	v_cvt_pk_bf16_f32 v5, v12, v13
	s_andn2_b64 vcc, exec, s[0:1]
	s_mov_b64 s[0:1], -1
	global_store_dwordx4 v[20:21], v[2:5], off offset:256
	s_cbranch_vccnz .LBB0_948
	s_andn2_b64 vcc, exec, s[8:9]
	s_cbranch_vccnz .LBB0_947
	s_barrier
	s_branch .LBB0_947
